# base9 + nt on the final output stores
# baseline (speedup 1.0000x reference)
; __device__ __forceinline__ void row_store(float* p, int lane, const f32x4 (&v)[4]) { f32x4* xr = (f32x4*)p + lane;
; #pragma unroll
;     for (int j = 0; j < 4; ++j) xr[64 * j] = v[j]; }
; __device__ __forceinline__ void phase_ln2(const Args& a, LAS unsigned char* lds, const WCtx& w, int l, int nrows) {
;     ...
;         if (l == DEPTH - 1) row_store(a.out + (size_t)row * 1024, w.lane, x);
.LBB0_2569:
	s_andn2_b64 vcc, exec, s[0:1]
	s_cbranch_vccnz .LBB0_2553
	s_ashr_i32 s5, s4, 31
	s_lshl_b64 s[0:1], s[4:5], 12
	v_lshl_add_u64 v[52:53], v[44:45], 0, s[0:1]
	global_store_dwordx4 v[52:53], v[18:21], off nt
	global_store_dwordx4 v[52:53], v[22:25], off offset:1024 nt
	global_store_dwordx4 v[52:53], v[26:29], off offset:2048 nt
	global_store_dwordx4 v[52:53], v[30:33], off offset:3072 nt
	s_branch .LBB0_2553
